# removable XNACK replay pad (s_nop 0) dropped from the MLA QK cluster load group
# baseline (speedup 1.0000x reference)
; template <int DK, int MODE> ...
;     ...
;   auto gload = [&](int jt) {
; #pragma unroll
;     for (int i = 0; i < NKL; ++i) {
;       const int id = tid + 256 * i, row = id / KCH, ch = id % KCH;
;       rk[i] = *(const u32x4*)(K + (size_t)(jt * 64 + row) * DK + ch * 8);
;     }
; #pragma unroll
;     for (int i = 0; i < 2; ++i) {
;       const int id = tid + 256 * i, row = id >> 3, ch = id & 7;
;       rv[i] = *(const u32x4*)(Vt + (size_t)row * Skv + jt * 64 + ch * 8);
;     }
;     if (MODE == 1) rf = F[jt * 64 + (tid & 63)];
;   };
;     ...
;     const bool active = !CAUSAL || (key0 <= tq0 + 31);
;     if (active) {
;       f32x16 s0, s1;
;       const bf16_t* kb = sK + cur * 64 * LDK + l32 * LDK + h * 8;
;       bf16x8 kf0[NKS], kf1[NKS];
; #pragma unroll
;       for (int ks = 0; ks < NKS; ++ks) { kf0[ks] = *(const bf16x8*)(kb + ks * 16); kf1[ks] = *(const bf16x8*)(kb + 32 * LDK + ks * 16); }
;       if (MODE == 1) {
;         const float* fb = sF + cur * 64 + 4 * h;
; #pragma unroll
;         for (int g = 0; g < 4; ++g) {
;           const f32x4 f0 = *(const f32x4*)(fb + 8 * g), f1 = *(const f32x4*)(fb + 32 + 8 * g);
;           s0[4 * g] = f0.x; s0[4 * g + 1] = f0.y; s0[4 * g + 2] = f0.z; s0[4 * g + 3] = f0.w;
;           s1[4 * g] = f1.x; s1[4 * g + 1] = f1.y; s1[4 * g + 2] = f1.z; s1[4 * g + 3] = f1.w;
;         }
;       } else {
; #pragma unroll
;         for (int e = 0; e < 16; ++e) { s0[e] = 0.f; s1[e] = 0.f; }
;       }
;       __builtin_amdgcn_iglp_opt(0);
;       __builtin_amdgcn_s_setprio(1);
; #pragma unroll
;       for (int ks = 0; ks < NKS; ++ks) { s0 = MFMA(kf0[ks], qf[ks], s0); s1 = MFMA(kf1[ks], qf[ks], s1); }
;       __builtin_amdgcn_s_setprio(0);
;       const bf16_t* vb = sV + cur * 64 * 72 + l32 * 72 + h * 8;
;       bf16x8 vf0[4], vf1[4];
; #pragma unroll
;       for (int j = 0; j < 4; ++j) { vf0[j] = *(const bf16x8*)(vb + j * 16); vf1[j] = *(const bf16x8*)(vb + 32 * 72 + j * 16); }
;       __builtin_amdgcn_sched_barrier(0);
;       const bool need_mask = CAUSAL && (key0 + 63 >= tq0);
;       bf16x8 pf[4];
;       if (MODE != 2) {
;         if (need_mask) {
; #pragma unroll
;           for (int e = 0; e < 16; ++e) {
;             const int key = key0 + 8 * (e >> 2) + 4 * h + (e & 3);
;             if (key > qpos) s0[e] = -1e30f;
;             if (key + 32 > qpos) s1[e] = -1e30f;
;           }
.LBB0_526:
	s_and_b32 s11, s10, 1
	s_cmp_gt_i32 s9, s8
	s_cbranch_scc1 .Lmla_inactive
	s_mul_i32 s12, s11, 0x3400
	v_add_u32_e32 v0, s12, v175
	ds_read_b128 v[48:51], v0 offset:6656
	ds_read_b128 v[52:55], v0
	ds_read_b128 v[92:95], v0 offset:32
	ds_read_b128 v[96:99], v0 offset:6688
	ds_read_b128 v[100:103], v0 offset:64
	ds_read_b128 v[104:107], v0 offset:6720
	ds_read_b128 v[108:111], v0 offset:96
	ds_read_b128 v[132:135], v0 offset:6752
	ds_read_b128 v[136:139], v0 offset:128
	ds_read_b128 v[140:143], v0 offset:6784
	ds_read_b128 v[176:179], v0 offset:160
	ds_read_b128 v[180:183], v0 offset:6816
	s_setprio 1
	s_waitcnt lgkmcnt(10)
	v_mfma_f32_32x32x16_bf16 v[64:79], v[52:55], v[80:83], 0
	s_mul_i32 s12, s11, 0x2400
	v_add_u32_e32 v0, s12, v157
	v_mfma_f32_32x32x16_bf16 v[48:63], v[48:51], v[80:83], 0
	global_load_dwordx4 v[88:91], v[170:171], off
	s_waitcnt lgkmcnt(9)
	v_mfma_f32_32x32x16_bf16 v[64:79], v[92:95], v[128:131], v[64:79]
	ds_read_b128 v[92:95], v0 offset:31328
	s_waitcnt lgkmcnt(9)
	v_mfma_f32_32x32x16_bf16 v[48:63], v[96:99], v[128:131], v[48:63]
	global_load_dwordx4 v[84:87], v[168:169], off
	ds_read_b128 v[96:99], v0 offset:26720
	s_waitcnt lgkmcnt(9)
	v_mfma_f32_32x32x16_bf16 v[64:79], v[100:103], v[124:127], v[64:79]
	ds_read_b128 v[100:103], v0 offset:26688
	s_waitcnt lgkmcnt(9)
	v_mfma_f32_32x32x16_bf16 v[48:63], v[104:107], v[124:127], v[48:63]
	global_load_dwordx4 v[10:13], v[166:167], off
	ds_read_b128 v[104:107], v0 offset:31296
	s_waitcnt lgkmcnt(9)
	v_mfma_f32_32x32x16_bf16 v[64:79], v[108:111], v[120:123], v[64:79]
	ds_read_b128 v[108:111], v0 offset:26656
	s_waitcnt lgkmcnt(9)
	v_mfma_f32_32x32x16_bf16 v[48:63], v[132:135], v[120:123], v[48:63]
	global_load_dwordx4 v[6:9], v[164:165], off
	ds_read_b128 v[132:135], v0 offset:31264
	s_waitcnt lgkmcnt(9)
	v_mfma_f32_32x32x16_bf16 v[64:79], v[136:139], v[116:119], v[64:79]
	ds_read_b128 v[136:139], v0 offset:26624
	s_waitcnt lgkmcnt(9)
	v_mfma_f32_32x32x16_bf16 v[48:63], v[140:143], v[116:119], v[48:63]
	global_load_dwordx4 v[2:5], v[162:163], off
	ds_read_b128 v[140:143], v0 offset:31232
	s_waitcnt lgkmcnt(9)
	v_mfma_f32_32x32x16_bf16 v[64:79], v[176:179], v[112:115], v[64:79]
	s_waitcnt lgkmcnt(8)
	v_mfma_f32_32x32x16_bf16 v[48:63], v[180:183], v[112:115], v[48:63]
	s_setprio 0
	s_add_i32 s12, s9, 63
	s_cmp_lt_i32 s12, s1
	s_cbranch_scc1 .LBB0_529
	v_add_u32_e32 v0, s9, v149
	v_add_u32_e32 v14, 32, v0
	v_cmp_le_i32_e32 vcc, v14, v152
	v_add_u32_e32 v14, 33, v0
	s_nop 4
	v_cndmask_b32_e32 v48, v198, v48, vcc
	v_cmp_lt_i32_e32 vcc, v0, v152
	s_nop 1
	v_cndmask_b32_e32 v65, v198, v65, vcc
	v_cmp_le_i32_e32 vcc, v0, v152
	s_nop 1
	v_cndmask_b32_e32 v64, v198, v64, vcc
	v_cmp_le_i32_e32 vcc, v14, v152
	v_add_u32_e32 v14, 2, v0
	s_nop 0
	v_cndmask_b32_e32 v49, v198, v49, vcc
	v_cmp_le_i32_e32 vcc, v14, v152
	v_add_u32_e32 v14, 34, v0
	s_nop 0
	v_cndmask_b32_e32 v66, v198, v66, vcc
	v_cmp_le_i32_e32 vcc, v14, v152
	v_add_u32_e32 v14, 3, v0
	s_nop 0
	v_cndmask_b32_e32 v50, v198, v50, vcc
	v_cmp_le_i32_e32 vcc, v14, v152
	v_add_u32_e32 v14, 35, v0
	s_nop 0
	v_cndmask_b32_e32 v67, v198, v67, vcc
	v_cmp_le_i32_e32 vcc, v14, v152
	v_add_u32_e32 v14, 8, v0
	s_nop 0
	v_cndmask_b32_e32 v51, v198, v51, vcc
	v_cmp_le_i32_e32 vcc, v14, v152
	v_add_u32_e32 v14, 40, v0
	s_nop 0
	v_cndmask_b32_e32 v68, v198, v68, vcc
	v_cmp_le_i32_e32 vcc, v14, v152
	v_add_u32_e32 v14, 9, v0
	s_nop 0
	v_cndmask_b32_e32 v52, v198, v52, vcc
	v_cmp_le_i32_e32 vcc, v14, v152
	v_add_u32_e32 v14, 41, v0
	s_nop 0
	v_cndmask_b32_e32 v69, v198, v69, vcc
	v_cmp_le_i32_e32 vcc, v14, v152
	v_add_u32_e32 v14, 10, v0
	s_nop 0
	v_cndmask_b32_e32 v53, v198, v53, vcc
	v_cmp_le_i32_e32 vcc, v14, v152
	v_add_u32_e32 v14, 42, v0
	s_nop 0
	v_cndmask_b32_e32 v70, v198, v70, vcc
	v_cmp_le_i32_e32 vcc, v14, v152
	v_add_u32_e32 v14, 11, v0
	s_nop 0
	v_cndmask_b32_e32 v54, v198, v54, vcc
	v_cmp_le_i32_e32 vcc, v14, v152
	v_add_u32_e32 v14, 43, v0
	s_nop 0
	v_cndmask_b32_e32 v71, v198, v71, vcc
	v_cmp_le_i32_e32 vcc, v14, v152
	v_add_u32_e32 v14, 16, v0
	s_nop 0
	v_cndmask_b32_e32 v55, v198, v55, vcc
	v_cmp_le_i32_e32 vcc, v14, v152
	v_add_u32_e32 v14, 48, v0
	s_nop 0
	v_cndmask_b32_e32 v72, v198, v72, vcc
	v_cmp_le_i32_e32 vcc, v14, v152
	v_add_u32_e32 v14, 17, v0
	s_nop 0
	v_cndmask_b32_e32 v56, v198, v56, vcc
	v_cmp_le_i32_e32 vcc, v14, v152
	v_add_u32_e32 v14, 49, v0
	s_nop 0
	v_cndmask_b32_e32 v73, v198, v73, vcc
	v_cmp_le_i32_e32 vcc, v14, v152
	v_add_u32_e32 v14, 18, v0
	s_nop 0
	v_cndmask_b32_e32 v57, v198, v57, vcc
	v_cmp_le_i32_e32 vcc, v14, v152
	v_add_u32_e32 v14, 50, v0
	s_nop 0
	v_cndmask_b32_e32 v74, v198, v74, vcc
	v_cmp_le_i32_e32 vcc, v14, v152
	v_add_u32_e32 v14, 19, v0
	s_nop 0
	v_cndmask_b32_e32 v58, v198, v58, vcc
	v_cmp_le_i32_e32 vcc, v14, v152
	v_add_u32_e32 v14, 51, v0
	s_nop 0
	v_cndmask_b32_e32 v75, v198, v75, vcc
	v_cmp_le_i32_e32 vcc, v14, v152
	v_add_u32_e32 v14, 24, v0
	s_nop 0
	v_cndmask_b32_e32 v59, v198, v59, vcc
	v_cmp_le_i32_e32 vcc, v14, v152
	v_add_u32_e32 v14, 56, v0
	s_nop 0
	v_cndmask_b32_e32 v76, v198, v76, vcc
	v_cmp_le_i32_e32 vcc, v14, v152
	v_add_u32_e32 v14, 25, v0
	s_nop 0
	v_cndmask_b32_e32 v60, v198, v60, vcc
	v_cmp_le_i32_e32 vcc, v14, v152
	v_add_u32_e32 v14, 57, v0
	s_nop 0
	v_cndmask_b32_e32 v77, v198, v77, vcc
	v_cmp_le_i32_e32 vcc, v14, v152
	v_add_u32_e32 v14, 26, v0
	s_nop 0
	v_cndmask_b32_e32 v61, v198, v61, vcc
	v_cmp_le_i32_e32 vcc, v14, v152
	v_add_u32_e32 v14, 58, v0
	s_nop 0
	v_cndmask_b32_e32 v78, v198, v78, vcc
	v_cmp_le_i32_e32 vcc, v14, v152
	v_add_u32_e32 v14, 27, v0
	v_add_u32_e32 v0, 59, v0
	v_cndmask_b32_e32 v62, v198, v62, vcc
	v_cmp_le_i32_e32 vcc, v14, v152
	s_nop 1
	v_cndmask_b32_e32 v79, v198, v79, vcc
	v_cmp_le_i32_e32 vcc, v0, v152
	s_nop 1
	v_cndmask_b32_e32 v63, v198, v63, vcc
